# v38 + scan C loop: per-chunk address copies removed, LDS ops address through running pointers (-7 VALU per chunk on the serial chain)
# speedup vs baseline: 1.0178x; 1.0039x over previous
.LBB0_580:
	ds_read2_b64 v[178:181], v42 offset1:4
	ds_read_b128 v[182:185], v82
	ds_read_b128 v[186:189], v82 offset:64
	ds_read2_b64 v[190:193], v42 offset0:8 offset1:12
	ds_read_b64_tr_b16 v[30:31], v83
	v_add_u32_e32 v83, 0x3700, v83
	ds_read2st64_b64 v[194:197], v85 offset1:1
	ds_read_b128 v[198:201], v43
	ds_read_b128 v[202:205], v82 offset:128
	ds_read_b64_tr_b16 v[158:159], v84 offset:6912
	ds_read_b64_tr_b16 v[162:163], v84 offset:6944
	ds_read_b64_tr_b16 v[166:167], v84 offset:6976
	s_waitcnt lgkmcnt(12)
	ds_read_b64_tr_b16 v[170:171], v84 offset:7008
	s_waitcnt lgkmcnt(12)
	ds_read_b64_tr_b16 v[38:39], v84 offset:4608
	s_waitcnt lgkmcnt(5)
	v_pk_mul_f32 v[16:17], v[16:17], v[202:203]
	v_add_u32_e32 v202, 0x800, v42
	v_add_u32_e32 v42, 0x3700, v42
	v_pk_mul_f32 v[18:19], v[18:19], v[204:205]
	v_pk_mul_f32 v[14:15], v[14:15], v[188:189]
	v_cvt_pk_f16_f32 v189, v18, v19
	v_cvt_pk_f16_f32 v188, v16, v17
	v_pk_mul_f32 v[6:7], v[6:7], v[184:185]
	v_pk_mul_f32 v[4:5], v[4:5], v[182:183]
	ds_read2st64_b64 v[182:185], v85 offset0:2 offset1:3
	v_add_u32_e32 v85, 0x3700, v85
	s_waitcnt lgkmcnt(2)
	v_mfma_f32_16x16x16_f16 v[170:173], v[170:171], v[30:31], v[16:19]
	v_pk_mul_f32 v[12:13], v[12:13], v[186:187]
	v_mfma_f32_16x16x16_f16 v[16:19], v[194:195], v[30:31], 0
	v_mul_f32_e64 v2, v2, v200
	v_mul_f32_e64 v3, v3, v201
	v_pk_mul_f32 v[0:1], v[0:1], v[198:199]
	v_cvt_pk_f16_f32 v187, v14, v15
	v_cvt_pk_f16_f32 v186, v12, v13
	v_cvt_pk_f16_f32 v201, v6, v7
	v_cvt_pk_f16_f32 v199, v2, v3
	v_cvt_pk_f16_f32 v200, v4, v5
	v_cvt_pk_f16_f32 v198, v0, v1
	v_mfma_f32_16x16x32_f16 v[190:193], v[190:193], v[186:189], 0
	v_mfma_f32_16x16x16_f16 v[162:165], v[162:163], v[30:31], v[4:7]
	v_mfma_f32_16x16x32_f16 v[4:7], v[178:181], v[198:201], v[16:19]
	v_mfma_f32_16x16x16_f16 v[12:15], v[166:167], v[30:31], v[12:15]
	ds_read_b64_tr_b16 v[174:175], v84 offset:4640
	ds_read2_b64 v[166:169], v202 offset0:40 offset1:44
	ds_read_b64_tr_b16 v[22:23], v84 offset:4672
	s_nop 3
	v_pk_add_f32 v[6:7], v[6:7], v[192:193]
	v_pk_add_f32 v[4:5], v[4:5], v[190:191]
	v_cvt_pk_f16_f32 v35, v6, v7
	v_cvt_pk_f16_f32 v34, v4, v5
	s_waitcnt lgkmcnt(3)
	s_nop 0
	v_mfma_f32_16x16x16_f16 v[4:7], v[184:185], v[34:35], 0
	v_mfma_f32_16x16x16_f16 v[158:161], v[158:159], v[30:31], v[0:3]
	s_nop 6
	v_xor_b32_e32 v16, 0x80000000, v7
	v_xor_b32_e32 v17, 0x80000000, v6
	v_xor_b32_e32 v5, 0x80000000, v5
	s_waitcnt lgkmcnt(1)
	v_mfma_f32_16x16x32_f16 v[0:3], v[166:169], v[186:189], 0
	v_xor_b32_e32 v4, 0x80000000, v4
	v_cvt_pk_f16_f32 v19, v17, v16
	v_cvt_pk_f16_f32 v18, v4, v5
	v_mfma_f32_16x16x16_f16 v[6:9], v[196:197], v[30:31], 0
	s_add_i32 s24, s24, -1
	v_mfma_f32_16x16x16_f16 v[30:33], v[38:39], v[18:19], v[158:161]
	ds_read_b64_tr_b16 v[26:27], v84 offset:4704
	v_add_u32_e32 v84, 0x3700, v84
	ds_read_b128 v[38:41], v43 offset:256
	v_add_u32_e32 v43, 0x3700, v43
	s_nop 0
	ds_read_b128 v[158:161], v82 offset:256
	v_mfma_f32_16x16x16_f16 v[34:37], v[174:175], v[18:19], v[162:165]
	s_waitcnt lgkmcnt(3)
	v_mfma_f32_16x16x16_f16 v[12:15], v[22:23], v[18:19], v[12:15]
	ds_read_b128 v[22:25], v82 offset:320
	ds_read_b128 v[162:165], v82 offset:384
	v_add_u32_e32 v82, 0x3700, v82
	v_mfma_f32_16x16x16_f16 v[166:169], v[182:183], v[18:19], v[0:3]
	s_waitcnt lgkmcnt(2)
	v_pk_mul_f32 v[4:5], v[158:159], v[34:35]
	ds_read2_b64 v[0:3], v202 offset0:32 offset1:36
	v_mfma_f32_16x16x16_f16 v[26:29], v[26:27], v[18:19], v[170:173]
	s_waitcnt lgkmcnt(2)
	v_pk_mul_f32 v[14:15], v[24:25], v[14:15]
	v_pk_mul_f32 v[12:13], v[22:23], v[12:13]
	s_waitcnt lgkmcnt(0)
	v_mfma_f32_16x16x32_f16 v[170:173], v[0:3], v[198:201], v[6:9]
	v_mul_f32_e64 v2, v40, v32
	v_mul_f32_e64 v3, v41, v33
	v_pk_mul_f32 v[0:1], v[38:39], v[30:31]
	v_pk_mul_f32 v[6:7], v[160:161], v[36:37]
	v_pk_mul_f32 v[18:19], v[164:165], v[28:29]
	v_pk_mul_f32 v[16:17], v[162:163], v[26:27]
	s_nop 1
	v_pk_add_f32 v[20:21], v[170:171], v[166:167]
	v_pk_add_f32 v[8:9], v[172:173], v[168:169]
	ds_write2st64_b32 v86, v20, v21 offset1:1
	ds_write2st64_b32 v86, v8, v9 offset0:2 offset1:3
	v_add_u32_e32 v86, 0x1000, v86
	s_cmp_lg_u32 s24, 0
	s_cbranch_scc1 .LBB0_580
